# prep token-mix section: nested exec-masked tanh/sigmoid blocks of the one wave that owns those columns replaced by a branch-free sequence with per-lane constants; other waves skip with one scalar bran
# baseline (speedup 1.0000x reference)
.LBB0_167:
	s_add_i32 s55, s55, s54
	s_cmpk_lt_i32 s55, 0x400
	s_cselect_b64 s[46:47], -1, 0
	s_cmpk_gt_i32 s55, 0x3ff
	v_mov_b32_e32 v111, v152
	s_cselect_b64 s[42:43], -1, 0
	s_nop 0
	v_cmp_gt_i32_e32 vcc, s57, v111
	v_lshlrev_b32_e32 v54, 1, v111
	s_barrier
	s_and_saveexec_b64 s[44:45], vcc
	s_cbranch_execz .LBB0_301
	s_waitcnt vmcnt(21)
	v_and_b32_e32 v57, 0xffff0000, v1
	v_lshlrev_b32_e32 v56, 16, v1
	v_and_b32_e32 v59, 0xffff0000, v0
	v_lshlrev_b32_e32 v58, 16, v0
	v_pk_add_f32 v[58:59], v[58:59], v[56:57] neg_lo:[0,1] neg_hi:[0,1]
	v_cmp_lt_i32_e64 s[6:7], s58, v111
	v_cmp_lt_u32_e64 s[4:5], s59, v111
	v_cmp_lt_u32_e32 vcc, s60, v111
	s_waitcnt vmcnt(5)
	v_pk_fma_f32 v[58:59], v[50:51], v[58:59], v[56:57]
	s_andn2_b64 s[94:95], s[6:7], s[4:5]
	s_or_b64 s[96:97], s[94:95], vcc
	s_nop 1
	v_cndmask_b32_e64 v236, 1.0, 2.0, s[94:95]
	v_cndmask_b32_e64 v238, 0, -1.0, s[94:95]
	s_cmp_eq_u64 s[6:7], 0
	s_cbranch_scc1 .Lpq0_0
	v_pk_mul_f32 v[234:235], v[58:59], v[236:237] op_sel_hi:[1,0]
	v_mul_f32_e32 v234, 0xbfb8aa3b, v234
	v_mul_f32_e32 v235, 0xbfb8aa3b, v235
	v_exp_f32_e32 v234, v234
	v_exp_f32_e32 v235, v235
	s_nop 0
	v_pk_add_f32 v[234:235], v[234:235], 1.0 op_sel_hi:[1,0]
	v_rcp_f32_e32 v234, v234
	v_rcp_f32_e32 v235, v235
	s_nop 0
	v_pk_fma_f32 v[234:235], v[234:235], v[236:237], v[238:239] op_sel_hi:[1,0,0]
	v_cndmask_b32_e64 v58, v58, v234, s[96:97]
	v_cndmask_b32_e64 v59, v59, v235, s[96:97]
.Lpq0_0:
	v_lshl_add_u32 v52, v54, 2, 0
	ds_write_b64 v52, v[58:59]
	v_and_b32_e32 v59, 0xffff0000, v2
	v_lshlrev_b32_e32 v58, 16, v2
	v_pk_add_f32 v[56:57], v[56:57], v[58:59] neg_lo:[0,1] neg_hi:[0,1]
	s_nop 0
	v_pk_fma_f32 v[56:57], v[50:51], v[56:57], v[58:59]
	s_cbranch_scc1 .Lpq0_1
	v_pk_mul_f32 v[234:235], v[56:57], v[236:237] op_sel_hi:[1,0]
	v_mul_f32_e32 v234, 0xbfb8aa3b, v234
	v_mul_f32_e32 v235, 0xbfb8aa3b, v235
	v_exp_f32_e32 v234, v234
	v_exp_f32_e32 v235, v235
	s_nop 0
	v_pk_add_f32 v[234:235], v[234:235], 1.0 op_sel_hi:[1,0]
	v_rcp_f32_e32 v234, v234
	v_rcp_f32_e32 v235, v235
	s_nop 0
	v_pk_fma_f32 v[234:235], v[234:235], v[236:237], v[238:239] op_sel_hi:[1,0,0]
	v_cndmask_b32_e64 v56, v56, v234, s[96:97]
	v_cndmask_b32_e64 v57, v57, v235, s[96:97]
.Lpq0_1:
	ds_write_b64 v52, v[56:57] offset:3600
	v_and_b32_e32 v57, 0xffff0000, v3
	v_lshlrev_b32_e32 v56, 16, v3
	v_pk_add_f32 v[58:59], v[58:59], v[56:57] neg_lo:[0,1] neg_hi:[0,1]
	s_nop 0
	v_pk_fma_f32 v[58:59], v[50:51], v[58:59], v[56:57]
	s_cbranch_scc1 .Lpq0_2
	v_pk_mul_f32 v[234:235], v[58:59], v[236:237] op_sel_hi:[1,0]
	v_mul_f32_e32 v234, 0xbfb8aa3b, v234
	v_mul_f32_e32 v235, 0xbfb8aa3b, v235
	v_exp_f32_e32 v234, v234
	v_exp_f32_e32 v235, v235
	s_nop 0
	v_pk_add_f32 v[234:235], v[234:235], 1.0 op_sel_hi:[1,0]
	v_rcp_f32_e32 v234, v234
	v_rcp_f32_e32 v235, v235
	s_nop 0
	v_pk_fma_f32 v[234:235], v[234:235], v[236:237], v[238:239] op_sel_hi:[1,0,0]
	v_cndmask_b32_e64 v58, v58, v234, s[96:97]
	v_cndmask_b32_e64 v59, v59, v235, s[96:97]
.Lpq0_2:
	ds_write_b64 v52, v[58:59] offset:7200
	v_and_b32_e32 v59, 0xffff0000, v4
	v_lshlrev_b32_e32 v58, 16, v4
	v_pk_add_f32 v[56:57], v[56:57], v[58:59] neg_lo:[0,1] neg_hi:[0,1]
	s_nop 0
	v_pk_fma_f32 v[56:57], v[50:51], v[56:57], v[58:59]
	s_cbranch_scc1 .Lpq0_3
	v_pk_mul_f32 v[234:235], v[56:57], v[236:237] op_sel_hi:[1,0]
	v_mul_f32_e32 v234, 0xbfb8aa3b, v234
	v_mul_f32_e32 v235, 0xbfb8aa3b, v235
	v_exp_f32_e32 v234, v234
	v_exp_f32_e32 v235, v235
	s_nop 0
	v_pk_add_f32 v[234:235], v[234:235], 1.0 op_sel_hi:[1,0]
	v_rcp_f32_e32 v234, v234
	v_rcp_f32_e32 v235, v235
	s_nop 0
	v_pk_fma_f32 v[234:235], v[234:235], v[236:237], v[238:239] op_sel_hi:[1,0,0]
	v_cndmask_b32_e64 v56, v56, v234, s[96:97]
	v_cndmask_b32_e64 v57, v57, v235, s[96:97]
.Lpq0_3:
	ds_write_b64 v52, v[56:57] offset:10800
	v_and_b32_e32 v57, 0xffff0000, v5
	v_lshlrev_b32_e32 v56, 16, v5
	v_pk_add_f32 v[58:59], v[58:59], v[56:57] neg_lo:[0,1] neg_hi:[0,1]
	s_nop 0
	v_pk_fma_f32 v[58:59], v[50:51], v[58:59], v[56:57]
	s_cbranch_scc1 .Lpq0_4
	v_pk_mul_f32 v[234:235], v[58:59], v[236:237] op_sel_hi:[1,0]
	v_mul_f32_e32 v234, 0xbfb8aa3b, v234
	v_mul_f32_e32 v235, 0xbfb8aa3b, v235
	v_exp_f32_e32 v234, v234
	v_exp_f32_e32 v235, v235
	s_nop 0
	v_pk_add_f32 v[234:235], v[234:235], 1.0 op_sel_hi:[1,0]
	v_rcp_f32_e32 v234, v234
	v_rcp_f32_e32 v235, v235
	s_nop 0
	v_pk_fma_f32 v[234:235], v[234:235], v[236:237], v[238:239] op_sel_hi:[1,0,0]
	v_cndmask_b32_e64 v58, v58, v234, s[96:97]
	v_cndmask_b32_e64 v59, v59, v235, s[96:97]
.Lpq0_4:
	ds_write_b64 v52, v[58:59] offset:14400
	v_and_b32_e32 v59, 0xffff0000, v6
	v_lshlrev_b32_e32 v58, 16, v6
	v_pk_add_f32 v[56:57], v[56:57], v[58:59] neg_lo:[0,1] neg_hi:[0,1]
	s_nop 0
	v_pk_fma_f32 v[56:57], v[50:51], v[56:57], v[58:59]
	s_cbranch_scc1 .Lpq0_5
	v_pk_mul_f32 v[234:235], v[56:57], v[236:237] op_sel_hi:[1,0]
	v_mul_f32_e32 v234, 0xbfb8aa3b, v234
	v_mul_f32_e32 v235, 0xbfb8aa3b, v235
	v_exp_f32_e32 v234, v234
	v_exp_f32_e32 v235, v235
	s_nop 0
	v_pk_add_f32 v[234:235], v[234:235], 1.0 op_sel_hi:[1,0]
	v_rcp_f32_e32 v234, v234
	v_rcp_f32_e32 v235, v235
	s_nop 0
	v_pk_fma_f32 v[234:235], v[234:235], v[236:237], v[238:239] op_sel_hi:[1,0,0]
	v_cndmask_b32_e64 v56, v56, v234, s[96:97]
	v_cndmask_b32_e64 v57, v57, v235, s[96:97]
.Lpq0_5:
	ds_write_b64 v52, v[56:57] offset:18000
	v_and_b32_e32 v57, 0xffff0000, v7
	v_lshlrev_b32_e32 v56, 16, v7
	v_pk_add_f32 v[58:59], v[58:59], v[56:57] neg_lo:[0,1] neg_hi:[0,1]
	s_nop 0
	v_pk_fma_f32 v[58:59], v[50:51], v[58:59], v[56:57]
	s_cbranch_scc1 .Lpq0_6
	v_pk_mul_f32 v[234:235], v[58:59], v[236:237] op_sel_hi:[1,0]
	v_mul_f32_e32 v234, 0xbfb8aa3b, v234
	v_mul_f32_e32 v235, 0xbfb8aa3b, v235
	v_exp_f32_e32 v234, v234
	v_exp_f32_e32 v235, v235
	s_nop 0
	v_pk_add_f32 v[234:235], v[234:235], 1.0 op_sel_hi:[1,0]
	v_rcp_f32_e32 v234, v234
	v_rcp_f32_e32 v235, v235
	s_nop 0
	v_pk_fma_f32 v[234:235], v[234:235], v[236:237], v[238:239] op_sel_hi:[1,0,0]
	v_cndmask_b32_e64 v58, v58, v234, s[96:97]
	v_cndmask_b32_e64 v59, v59, v235, s[96:97]
.Lpq0_6:
	ds_write_b64 v52, v[58:59] offset:21600
	v_and_b32_e32 v59, 0xffff0000, v8
	v_lshlrev_b32_e32 v58, 16, v8
	v_pk_add_f32 v[56:57], v[56:57], v[58:59] neg_lo:[0,1] neg_hi:[0,1]
	s_nop 0
	v_pk_fma_f32 v[56:57], v[50:51], v[56:57], v[58:59]
	s_cbranch_scc1 .Lpq0_7
	v_pk_mul_f32 v[234:235], v[56:57], v[236:237] op_sel_hi:[1,0]
	v_mul_f32_e32 v234, 0xbfb8aa3b, v234
	v_mul_f32_e32 v235, 0xbfb8aa3b, v235
	v_exp_f32_e32 v234, v234
	v_exp_f32_e32 v235, v235
	s_nop 0
	v_pk_add_f32 v[234:235], v[234:235], 1.0 op_sel_hi:[1,0]
	v_rcp_f32_e32 v234, v234
	v_rcp_f32_e32 v235, v235
	s_nop 0
	v_pk_fma_f32 v[234:235], v[234:235], v[236:237], v[238:239] op_sel_hi:[1,0,0]
	v_cndmask_b32_e64 v56, v56, v234, s[96:97]
	v_cndmask_b32_e64 v57, v57, v235, s[96:97]
.Lpq0_7:
	ds_write_b64 v52, v[56:57] offset:25200
	v_and_b32_e32 v57, 0xffff0000, v9
	v_lshlrev_b32_e32 v56, 16, v9
	v_pk_add_f32 v[58:59], v[58:59], v[56:57] neg_lo:[0,1] neg_hi:[0,1]
	s_nop 0
	v_pk_fma_f32 v[58:59], v[50:51], v[58:59], v[56:57]
	s_cbranch_scc1 .Lpq0_8
	v_pk_mul_f32 v[234:235], v[58:59], v[236:237] op_sel_hi:[1,0]
	v_mul_f32_e32 v234, 0xbfb8aa3b, v234
	v_mul_f32_e32 v235, 0xbfb8aa3b, v235
	v_exp_f32_e32 v234, v234
	v_exp_f32_e32 v235, v235
	s_nop 0
	v_pk_add_f32 v[234:235], v[234:235], 1.0 op_sel_hi:[1,0]
	v_rcp_f32_e32 v234, v234
	v_rcp_f32_e32 v235, v235
	s_nop 0
	v_pk_fma_f32 v[234:235], v[234:235], v[236:237], v[238:239] op_sel_hi:[1,0,0]
	v_cndmask_b32_e64 v58, v58, v234, s[96:97]
	v_cndmask_b32_e64 v59, v59, v235, s[96:97]
.Lpq0_8:
	ds_write_b64 v52, v[58:59] offset:28800
	v_and_b32_e32 v59, 0xffff0000, v10
	v_lshlrev_b32_e32 v58, 16, v10
	v_pk_add_f32 v[56:57], v[56:57], v[58:59] neg_lo:[0,1] neg_hi:[0,1]
	s_nop 0
	v_pk_fma_f32 v[56:57], v[50:51], v[56:57], v[58:59]
	s_cbranch_scc1 .Lpq0_9
	v_pk_mul_f32 v[234:235], v[56:57], v[236:237] op_sel_hi:[1,0]
	v_mul_f32_e32 v234, 0xbfb8aa3b, v234
	v_mul_f32_e32 v235, 0xbfb8aa3b, v235
	v_exp_f32_e32 v234, v234
	v_exp_f32_e32 v235, v235
	s_nop 0
	v_pk_add_f32 v[234:235], v[234:235], 1.0 op_sel_hi:[1,0]
	v_rcp_f32_e32 v234, v234
	v_rcp_f32_e32 v235, v235
	s_nop 0
	v_pk_fma_f32 v[234:235], v[234:235], v[236:237], v[238:239] op_sel_hi:[1,0,0]
	v_cndmask_b32_e64 v56, v56, v234, s[96:97]
	v_cndmask_b32_e64 v57, v57, v235, s[96:97]
.Lpq0_9:
	ds_write_b64 v52, v[56:57] offset:32400
	v_and_b32_e32 v57, 0xffff0000, v11
	v_lshlrev_b32_e32 v56, 16, v11
	v_pk_add_f32 v[58:59], v[58:59], v[56:57] neg_lo:[0,1] neg_hi:[0,1]
	s_nop 0
	v_pk_fma_f32 v[58:59], v[50:51], v[58:59], v[56:57]
	s_cbranch_scc1 .Lpq0_10
	v_pk_mul_f32 v[234:235], v[58:59], v[236:237] op_sel_hi:[1,0]
	v_mul_f32_e32 v234, 0xbfb8aa3b, v234
	v_mul_f32_e32 v235, 0xbfb8aa3b, v235
	v_exp_f32_e32 v234, v234
	v_exp_f32_e32 v235, v235
	s_nop 0
	v_pk_add_f32 v[234:235], v[234:235], 1.0 op_sel_hi:[1,0]
	v_rcp_f32_e32 v234, v234
	v_rcp_f32_e32 v235, v235
	s_nop 0
	v_pk_fma_f32 v[234:235], v[234:235], v[236:237], v[238:239] op_sel_hi:[1,0,0]
	v_cndmask_b32_e64 v58, v58, v234, s[96:97]
	v_cndmask_b32_e64 v59, v59, v235, s[96:97]
.Lpq0_10:
	ds_write_b64 v52, v[58:59] offset:36000
	v_and_b32_e32 v59, 0xffff0000, v12
	v_lshlrev_b32_e32 v58, 16, v12
	v_pk_add_f32 v[56:57], v[56:57], v[58:59] neg_lo:[0,1] neg_hi:[0,1]
	s_nop 0
	v_pk_fma_f32 v[56:57], v[50:51], v[56:57], v[58:59]
	s_cbranch_scc1 .Lpq0_11
	v_pk_mul_f32 v[234:235], v[56:57], v[236:237] op_sel_hi:[1,0]
	v_mul_f32_e32 v234, 0xbfb8aa3b, v234
	v_mul_f32_e32 v235, 0xbfb8aa3b, v235
	v_exp_f32_e32 v234, v234
	v_exp_f32_e32 v235, v235
	s_nop 0
	v_pk_add_f32 v[234:235], v[234:235], 1.0 op_sel_hi:[1,0]
	v_rcp_f32_e32 v234, v234
	v_rcp_f32_e32 v235, v235
	s_nop 0
	v_pk_fma_f32 v[234:235], v[234:235], v[236:237], v[238:239] op_sel_hi:[1,0,0]
	v_cndmask_b32_e64 v56, v56, v234, s[96:97]
	v_cndmask_b32_e64 v57, v57, v235, s[96:97]
.Lpq0_11:
	ds_write_b64 v52, v[56:57] offset:39600
	v_and_b32_e32 v57, 0xffff0000, v13
	v_lshlrev_b32_e32 v56, 16, v13
	v_pk_add_f32 v[58:59], v[58:59], v[56:57] neg_lo:[0,1] neg_hi:[0,1]
	s_nop 0
	v_pk_fma_f32 v[58:59], v[50:51], v[58:59], v[56:57]
	s_cbranch_scc1 .Lpq0_12
	v_pk_mul_f32 v[234:235], v[58:59], v[236:237] op_sel_hi:[1,0]
	v_mul_f32_e32 v234, 0xbfb8aa3b, v234
	v_mul_f32_e32 v235, 0xbfb8aa3b, v235
	v_exp_f32_e32 v234, v234
	v_exp_f32_e32 v235, v235
	s_nop 0
	v_pk_add_f32 v[234:235], v[234:235], 1.0 op_sel_hi:[1,0]
	v_rcp_f32_e32 v234, v234
	v_rcp_f32_e32 v235, v235
	s_nop 0
	v_pk_fma_f32 v[234:235], v[234:235], v[236:237], v[238:239] op_sel_hi:[1,0,0]
	v_cndmask_b32_e64 v58, v58, v234, s[96:97]
	v_cndmask_b32_e64 v59, v59, v235, s[96:97]
.Lpq0_12:
	ds_write_b64 v52, v[58:59] offset:43200
	v_and_b32_e32 v59, 0xffff0000, v14
	v_lshlrev_b32_e32 v58, 16, v14
	v_pk_add_f32 v[56:57], v[56:57], v[58:59] neg_lo:[0,1] neg_hi:[0,1]
	s_nop 0
	v_pk_fma_f32 v[56:57], v[50:51], v[56:57], v[58:59]
	s_cbranch_scc1 .Lpq0_13
	v_pk_mul_f32 v[234:235], v[56:57], v[236:237] op_sel_hi:[1,0]
	v_mul_f32_e32 v234, 0xbfb8aa3b, v234
	v_mul_f32_e32 v235, 0xbfb8aa3b, v235
	v_exp_f32_e32 v234, v234
	v_exp_f32_e32 v235, v235
	s_nop 0
	v_pk_add_f32 v[234:235], v[234:235], 1.0 op_sel_hi:[1,0]
	v_rcp_f32_e32 v234, v234
	v_rcp_f32_e32 v235, v235
	s_nop 0
	v_pk_fma_f32 v[234:235], v[234:235], v[236:237], v[238:239] op_sel_hi:[1,0,0]
	v_cndmask_b32_e64 v56, v56, v234, s[96:97]
	v_cndmask_b32_e64 v57, v57, v235, s[96:97]
.Lpq0_13:
	ds_write_b64 v52, v[56:57] offset:46800
	v_and_b32_e32 v57, 0xffff0000, v15
	v_lshlrev_b32_e32 v56, 16, v15
	v_pk_add_f32 v[58:59], v[58:59], v[56:57] neg_lo:[0,1] neg_hi:[0,1]
	s_nop 0
	v_pk_fma_f32 v[58:59], v[50:51], v[58:59], v[56:57]
	s_cbranch_scc1 .Lpq0_14
	v_pk_mul_f32 v[234:235], v[58:59], v[236:237] op_sel_hi:[1,0]
	v_mul_f32_e32 v234, 0xbfb8aa3b, v234
	v_mul_f32_e32 v235, 0xbfb8aa3b, v235
	v_exp_f32_e32 v234, v234
	v_exp_f32_e32 v235, v235
	s_nop 0
	v_pk_add_f32 v[234:235], v[234:235], 1.0 op_sel_hi:[1,0]
	v_rcp_f32_e32 v234, v234
	v_rcp_f32_e32 v235, v235
	s_nop 0
	v_pk_fma_f32 v[234:235], v[234:235], v[236:237], v[238:239] op_sel_hi:[1,0,0]
	v_cndmask_b32_e64 v58, v58, v234, s[96:97]
	v_cndmask_b32_e64 v59, v59, v235, s[96:97]
.Lpq0_14:
	ds_write_b64 v52, v[58:59] offset:50400
	v_and_b32_e32 v59, 0xffff0000, v16
	v_lshlrev_b32_e32 v58, 16, v16
	v_pk_add_f32 v[56:57], v[56:57], v[58:59] neg_lo:[0,1] neg_hi:[0,1]
	s_nop 0
	v_pk_fma_f32 v[56:57], v[50:51], v[56:57], v[58:59]
	s_cbranch_scc1 .Lpq0_15
	v_pk_mul_f32 v[234:235], v[56:57], v[236:237] op_sel_hi:[1,0]
	v_mul_f32_e32 v234, 0xbfb8aa3b, v234
	v_mul_f32_e32 v235, 0xbfb8aa3b, v235
	v_exp_f32_e32 v234, v234
	v_exp_f32_e32 v235, v235
	s_nop 0
	v_pk_add_f32 v[234:235], v[234:235], 1.0 op_sel_hi:[1,0]
	v_rcp_f32_e32 v234, v234
	v_rcp_f32_e32 v235, v235
	s_nop 0
	v_pk_fma_f32 v[234:235], v[234:235], v[236:237], v[238:239] op_sel_hi:[1,0,0]
	v_cndmask_b32_e64 v56, v56, v234, s[96:97]
	v_cndmask_b32_e64 v57, v57, v235, s[96:97]
.Lpq0_15:
	s_and_b64 s[4:5], s[46:47], exec
	s_cselect_b32 s4, s55, -1
	s_cmp_lt_i32 s4, 0
	ds_write_b64 v52, v[56:57] offset:54000
	s_cbranch_scc1 .LBB0_301
	s_lshl_b32 s10, s4, 4
	s_and_b32 s4, s4, 0xff
	s_cmp_lg_u32 s4, 0
	v_ashrrev_i32_e32 v55, 31, v54
	s_cbranch_scc0 .LBB0_325
	s_add_i32 s4, s10, -1
	s_mov_b32 s5, s11
	s_lshl_b64 s[4:5], s[4:5], 11
	s_add_u32 s4, s8, s4
	s_addc_u32 s5, s9, s5
	v_lshl_add_u64 v[0:1], v[54:55], 1, s[4:5]
	global_load_dword v0, v[0:1], off
	s_cbranch_execnz .LBB0_300

.LBB0_1049:
	s_add_i32 s55, s55, s54
	s_cmpk_lt_i32 s55, 0x400
	s_cselect_b64 s[46:47], -1, 0
	s_cmpk_gt_i32 s55, 0x3ff
	v_mov_b32_e32 v139, v152
	s_cselect_b64 s[42:43], -1, 0
	s_nop 0
	v_cmp_gt_i32_e32 vcc, s57, v139
	v_lshlrev_b32_e32 v70, 1, v139
	s_barrier
	s_and_saveexec_b64 s[44:45], vcc
	s_cbranch_execz .LBB0_1183
	s_waitcnt vmcnt(22)
	v_and_b32_e32 v73, 0xffff0000, v1
	v_lshlrev_b32_e32 v72, 16, v1
	v_and_b32_e32 v75, 0xffff0000, v0
	v_lshlrev_b32_e32 v74, 16, v0
	v_pk_add_f32 v[74:75], v[74:75], v[72:73] neg_lo:[0,1] neg_hi:[0,1]
	v_cmp_lt_i32_e64 s[6:7], s58, v139
	v_cmp_lt_u32_e64 s[4:5], s59, v139
	v_cmp_lt_u32_e32 vcc, s60, v139
	s_waitcnt vmcnt(6)
	v_pk_fma_f32 v[74:75], v[66:67], v[74:75], v[72:73]
	s_andn2_b64 s[94:95], s[6:7], s[4:5]
	s_or_b64 s[96:97], s[94:95], vcc
	s_nop 1
	v_cndmask_b32_e64 v236, 1.0, 2.0, s[94:95]
	v_cndmask_b32_e64 v238, 0, -1.0, s[94:95]
	s_cmp_eq_u64 s[6:7], 0
	s_cbranch_scc1 .Lpq1_0
	v_pk_mul_f32 v[234:235], v[74:75], v[236:237] op_sel_hi:[1,0]
	v_mul_f32_e32 v234, 0xbfb8aa3b, v234
	v_mul_f32_e32 v235, 0xbfb8aa3b, v235
	v_exp_f32_e32 v234, v234
	v_exp_f32_e32 v235, v235
	s_nop 0
	v_pk_add_f32 v[234:235], v[234:235], 1.0 op_sel_hi:[1,0]
	v_rcp_f32_e32 v234, v234
	v_rcp_f32_e32 v235, v235
	s_nop 0
	v_pk_fma_f32 v[234:235], v[234:235], v[236:237], v[238:239] op_sel_hi:[1,0,0]
	v_cndmask_b32_e64 v74, v74, v234, s[96:97]
	v_cndmask_b32_e64 v75, v75, v235, s[96:97]
.Lpq1_0:
	v_lshl_add_u32 v68, v70, 2, 0
	ds_write_b64 v68, v[74:75]
	v_and_b32_e32 v75, 0xffff0000, v2
	v_lshlrev_b32_e32 v74, 16, v2
	v_pk_add_f32 v[72:73], v[72:73], v[74:75] neg_lo:[0,1] neg_hi:[0,1]
	s_nop 0
	v_pk_fma_f32 v[72:73], v[66:67], v[72:73], v[74:75]
	s_cbranch_scc1 .Lpq1_1
	v_pk_mul_f32 v[234:235], v[72:73], v[236:237] op_sel_hi:[1,0]
	v_mul_f32_e32 v234, 0xbfb8aa3b, v234
	v_mul_f32_e32 v235, 0xbfb8aa3b, v235
	v_exp_f32_e32 v234, v234
	v_exp_f32_e32 v235, v235
	s_nop 0
	v_pk_add_f32 v[234:235], v[234:235], 1.0 op_sel_hi:[1,0]
	v_rcp_f32_e32 v234, v234
	v_rcp_f32_e32 v235, v235
	s_nop 0
	v_pk_fma_f32 v[234:235], v[234:235], v[236:237], v[238:239] op_sel_hi:[1,0,0]
	v_cndmask_b32_e64 v72, v72, v234, s[96:97]
	v_cndmask_b32_e64 v73, v73, v235, s[96:97]
.Lpq1_1:
	ds_write_b64 v68, v[72:73] offset:3600
	v_and_b32_e32 v73, 0xffff0000, v3
	v_lshlrev_b32_e32 v72, 16, v3
	v_pk_add_f32 v[74:75], v[74:75], v[72:73] neg_lo:[0,1] neg_hi:[0,1]
	s_nop 0
	v_pk_fma_f32 v[74:75], v[66:67], v[74:75], v[72:73]
	s_cbranch_scc1 .Lpq1_2
	v_pk_mul_f32 v[234:235], v[74:75], v[236:237] op_sel_hi:[1,0]
	v_mul_f32_e32 v234, 0xbfb8aa3b, v234
	v_mul_f32_e32 v235, 0xbfb8aa3b, v235
	v_exp_f32_e32 v234, v234
	v_exp_f32_e32 v235, v235
	s_nop 0
	v_pk_add_f32 v[234:235], v[234:235], 1.0 op_sel_hi:[1,0]
	v_rcp_f32_e32 v234, v234
	v_rcp_f32_e32 v235, v235
	s_nop 0
	v_pk_fma_f32 v[234:235], v[234:235], v[236:237], v[238:239] op_sel_hi:[1,0,0]
	v_cndmask_b32_e64 v74, v74, v234, s[96:97]
	v_cndmask_b32_e64 v75, v75, v235, s[96:97]
.Lpq1_2:
	ds_write_b64 v68, v[74:75] offset:7200
	v_and_b32_e32 v75, 0xffff0000, v4
	v_lshlrev_b32_e32 v74, 16, v4
	v_pk_add_f32 v[72:73], v[72:73], v[74:75] neg_lo:[0,1] neg_hi:[0,1]
	s_nop 0
	v_pk_fma_f32 v[72:73], v[66:67], v[72:73], v[74:75]
	s_cbranch_scc1 .Lpq1_3
	v_pk_mul_f32 v[234:235], v[72:73], v[236:237] op_sel_hi:[1,0]
	v_mul_f32_e32 v234, 0xbfb8aa3b, v234
	v_mul_f32_e32 v235, 0xbfb8aa3b, v235
	v_exp_f32_e32 v234, v234
	v_exp_f32_e32 v235, v235
	s_nop 0
	v_pk_add_f32 v[234:235], v[234:235], 1.0 op_sel_hi:[1,0]
	v_rcp_f32_e32 v234, v234
	v_rcp_f32_e32 v235, v235
	s_nop 0
	v_pk_fma_f32 v[234:235], v[234:235], v[236:237], v[238:239] op_sel_hi:[1,0,0]
	v_cndmask_b32_e64 v72, v72, v234, s[96:97]
	v_cndmask_b32_e64 v73, v73, v235, s[96:97]
.Lpq1_3:
	ds_write_b64 v68, v[72:73] offset:10800
	v_and_b32_e32 v73, 0xffff0000, v5
	v_lshlrev_b32_e32 v72, 16, v5
	v_pk_add_f32 v[74:75], v[74:75], v[72:73] neg_lo:[0,1] neg_hi:[0,1]
	s_nop 0
	v_pk_fma_f32 v[74:75], v[66:67], v[74:75], v[72:73]
	s_cbranch_scc1 .Lpq1_4
	v_pk_mul_f32 v[234:235], v[74:75], v[236:237] op_sel_hi:[1,0]
	v_mul_f32_e32 v234, 0xbfb8aa3b, v234
	v_mul_f32_e32 v235, 0xbfb8aa3b, v235
	v_exp_f32_e32 v234, v234
	v_exp_f32_e32 v235, v235
	s_nop 0
	v_pk_add_f32 v[234:235], v[234:235], 1.0 op_sel_hi:[1,0]
	v_rcp_f32_e32 v234, v234
	v_rcp_f32_e32 v235, v235
	s_nop 0
	v_pk_fma_f32 v[234:235], v[234:235], v[236:237], v[238:239] op_sel_hi:[1,0,0]
	v_cndmask_b32_e64 v74, v74, v234, s[96:97]
	v_cndmask_b32_e64 v75, v75, v235, s[96:97]
.Lpq1_4:
	ds_write_b64 v68, v[74:75] offset:14400
	v_and_b32_e32 v75, 0xffff0000, v6
	v_lshlrev_b32_e32 v74, 16, v6
	v_pk_add_f32 v[72:73], v[72:73], v[74:75] neg_lo:[0,1] neg_hi:[0,1]
	s_nop 0
	v_pk_fma_f32 v[72:73], v[66:67], v[72:73], v[74:75]
	s_cbranch_scc1 .Lpq1_5
	v_pk_mul_f32 v[234:235], v[72:73], v[236:237] op_sel_hi:[1,0]
	v_mul_f32_e32 v234, 0xbfb8aa3b, v234
	v_mul_f32_e32 v235, 0xbfb8aa3b, v235
	v_exp_f32_e32 v234, v234
	v_exp_f32_e32 v235, v235
	s_nop 0
	v_pk_add_f32 v[234:235], v[234:235], 1.0 op_sel_hi:[1,0]
	v_rcp_f32_e32 v234, v234
	v_rcp_f32_e32 v235, v235
	s_nop 0
	v_pk_fma_f32 v[234:235], v[234:235], v[236:237], v[238:239] op_sel_hi:[1,0,0]
	v_cndmask_b32_e64 v72, v72, v234, s[96:97]
	v_cndmask_b32_e64 v73, v73, v235, s[96:97]
.Lpq1_5:
	ds_write_b64 v68, v[72:73] offset:18000
	v_and_b32_e32 v73, 0xffff0000, v7
	v_lshlrev_b32_e32 v72, 16, v7
	v_pk_add_f32 v[74:75], v[74:75], v[72:73] neg_lo:[0,1] neg_hi:[0,1]
	s_nop 0
	v_pk_fma_f32 v[74:75], v[66:67], v[74:75], v[72:73]
	s_cbranch_scc1 .Lpq1_6
	v_pk_mul_f32 v[234:235], v[74:75], v[236:237] op_sel_hi:[1,0]
	v_mul_f32_e32 v234, 0xbfb8aa3b, v234
	v_mul_f32_e32 v235, 0xbfb8aa3b, v235
	v_exp_f32_e32 v234, v234
	v_exp_f32_e32 v235, v235
	s_nop 0
	v_pk_add_f32 v[234:235], v[234:235], 1.0 op_sel_hi:[1,0]
	v_rcp_f32_e32 v234, v234
	v_rcp_f32_e32 v235, v235
	s_nop 0
	v_pk_fma_f32 v[234:235], v[234:235], v[236:237], v[238:239] op_sel_hi:[1,0,0]
	v_cndmask_b32_e64 v74, v74, v234, s[96:97]
	v_cndmask_b32_e64 v75, v75, v235, s[96:97]
.Lpq1_6:
	ds_write_b64 v68, v[74:75] offset:21600
	v_and_b32_e32 v75, 0xffff0000, v8
	v_lshlrev_b32_e32 v74, 16, v8
	v_pk_add_f32 v[72:73], v[72:73], v[74:75] neg_lo:[0,1] neg_hi:[0,1]
	s_nop 0
	v_pk_fma_f32 v[72:73], v[66:67], v[72:73], v[74:75]
	s_cbranch_scc1 .Lpq1_7
	v_pk_mul_f32 v[234:235], v[72:73], v[236:237] op_sel_hi:[1,0]
	v_mul_f32_e32 v234, 0xbfb8aa3b, v234
	v_mul_f32_e32 v235, 0xbfb8aa3b, v235
	v_exp_f32_e32 v234, v234
	v_exp_f32_e32 v235, v235
	s_nop 0
	v_pk_add_f32 v[234:235], v[234:235], 1.0 op_sel_hi:[1,0]
	v_rcp_f32_e32 v234, v234
	v_rcp_f32_e32 v235, v235
	s_nop 0
	v_pk_fma_f32 v[234:235], v[234:235], v[236:237], v[238:239] op_sel_hi:[1,0,0]
	v_cndmask_b32_e64 v72, v72, v234, s[96:97]
	v_cndmask_b32_e64 v73, v73, v235, s[96:97]
.Lpq1_7:
	ds_write_b64 v68, v[72:73] offset:25200
	v_and_b32_e32 v73, 0xffff0000, v9
	v_lshlrev_b32_e32 v72, 16, v9
	v_pk_add_f32 v[74:75], v[74:75], v[72:73] neg_lo:[0,1] neg_hi:[0,1]
	s_nop 0
	v_pk_fma_f32 v[74:75], v[66:67], v[74:75], v[72:73]
	s_cbranch_scc1 .Lpq1_8
	v_pk_mul_f32 v[234:235], v[74:75], v[236:237] op_sel_hi:[1,0]
	v_mul_f32_e32 v234, 0xbfb8aa3b, v234
	v_mul_f32_e32 v235, 0xbfb8aa3b, v235
	v_exp_f32_e32 v234, v234
	v_exp_f32_e32 v235, v235
	s_nop 0
	v_pk_add_f32 v[234:235], v[234:235], 1.0 op_sel_hi:[1,0]
	v_rcp_f32_e32 v234, v234
	v_rcp_f32_e32 v235, v235
	s_nop 0
	v_pk_fma_f32 v[234:235], v[234:235], v[236:237], v[238:239] op_sel_hi:[1,0,0]
	v_cndmask_b32_e64 v74, v74, v234, s[96:97]
	v_cndmask_b32_e64 v75, v75, v235, s[96:97]
.Lpq1_8:
	ds_write_b64 v68, v[74:75] offset:28800
	v_and_b32_e32 v75, 0xffff0000, v10
	v_lshlrev_b32_e32 v74, 16, v10
	v_pk_add_f32 v[72:73], v[72:73], v[74:75] neg_lo:[0,1] neg_hi:[0,1]
	s_nop 0
	v_pk_fma_f32 v[72:73], v[66:67], v[72:73], v[74:75]
	s_cbranch_scc1 .Lpq1_9
	v_pk_mul_f32 v[234:235], v[72:73], v[236:237] op_sel_hi:[1,0]
	v_mul_f32_e32 v234, 0xbfb8aa3b, v234
	v_mul_f32_e32 v235, 0xbfb8aa3b, v235
	v_exp_f32_e32 v234, v234
	v_exp_f32_e32 v235, v235
	s_nop 0
	v_pk_add_f32 v[234:235], v[234:235], 1.0 op_sel_hi:[1,0]
	v_rcp_f32_e32 v234, v234
	v_rcp_f32_e32 v235, v235
	s_nop 0
	v_pk_fma_f32 v[234:235], v[234:235], v[236:237], v[238:239] op_sel_hi:[1,0,0]
	v_cndmask_b32_e64 v72, v72, v234, s[96:97]
	v_cndmask_b32_e64 v73, v73, v235, s[96:97]
.Lpq1_9:
	ds_write_b64 v68, v[72:73] offset:32400
	v_and_b32_e32 v73, 0xffff0000, v11
	v_lshlrev_b32_e32 v72, 16, v11
	v_pk_add_f32 v[74:75], v[74:75], v[72:73] neg_lo:[0,1] neg_hi:[0,1]
	s_nop 0
	v_pk_fma_f32 v[74:75], v[66:67], v[74:75], v[72:73]
	s_cbranch_scc1 .Lpq1_10
	v_pk_mul_f32 v[234:235], v[74:75], v[236:237] op_sel_hi:[1,0]
	v_mul_f32_e32 v234, 0xbfb8aa3b, v234
	v_mul_f32_e32 v235, 0xbfb8aa3b, v235
	v_exp_f32_e32 v234, v234
	v_exp_f32_e32 v235, v235
	s_nop 0
	v_pk_add_f32 v[234:235], v[234:235], 1.0 op_sel_hi:[1,0]
	v_rcp_f32_e32 v234, v234
	v_rcp_f32_e32 v235, v235
	s_nop 0
	v_pk_fma_f32 v[234:235], v[234:235], v[236:237], v[238:239] op_sel_hi:[1,0,0]
	v_cndmask_b32_e64 v74, v74, v234, s[96:97]
	v_cndmask_b32_e64 v75, v75, v235, s[96:97]
.Lpq1_10:
	ds_write_b64 v68, v[74:75] offset:36000
	v_and_b32_e32 v75, 0xffff0000, v12
	v_lshlrev_b32_e32 v74, 16, v12
	v_pk_add_f32 v[72:73], v[72:73], v[74:75] neg_lo:[0,1] neg_hi:[0,1]
	s_nop 0
	v_pk_fma_f32 v[72:73], v[66:67], v[72:73], v[74:75]
	s_cbranch_scc1 .Lpq1_11
	v_pk_mul_f32 v[234:235], v[72:73], v[236:237] op_sel_hi:[1,0]
	v_mul_f32_e32 v234, 0xbfb8aa3b, v234
	v_mul_f32_e32 v235, 0xbfb8aa3b, v235
	v_exp_f32_e32 v234, v234
	v_exp_f32_e32 v235, v235
	s_nop 0
	v_pk_add_f32 v[234:235], v[234:235], 1.0 op_sel_hi:[1,0]
	v_rcp_f32_e32 v234, v234
	v_rcp_f32_e32 v235, v235
	s_nop 0
	v_pk_fma_f32 v[234:235], v[234:235], v[236:237], v[238:239] op_sel_hi:[1,0,0]
	v_cndmask_b32_e64 v72, v72, v234, s[96:97]
	v_cndmask_b32_e64 v73, v73, v235, s[96:97]
.Lpq1_11:
	ds_write_b64 v68, v[72:73] offset:39600
	v_and_b32_e32 v73, 0xffff0000, v13
	v_lshlrev_b32_e32 v72, 16, v13
	v_pk_add_f32 v[74:75], v[74:75], v[72:73] neg_lo:[0,1] neg_hi:[0,1]
	s_nop 0
	v_pk_fma_f32 v[74:75], v[66:67], v[74:75], v[72:73]
	s_cbranch_scc1 .Lpq1_12
	v_pk_mul_f32 v[234:235], v[74:75], v[236:237] op_sel_hi:[1,0]
	v_mul_f32_e32 v234, 0xbfb8aa3b, v234
	v_mul_f32_e32 v235, 0xbfb8aa3b, v235
	v_exp_f32_e32 v234, v234
	v_exp_f32_e32 v235, v235
	s_nop 0
	v_pk_add_f32 v[234:235], v[234:235], 1.0 op_sel_hi:[1,0]
	v_rcp_f32_e32 v234, v234
	v_rcp_f32_e32 v235, v235
	s_nop 0
	v_pk_fma_f32 v[234:235], v[234:235], v[236:237], v[238:239] op_sel_hi:[1,0,0]
	v_cndmask_b32_e64 v74, v74, v234, s[96:97]
	v_cndmask_b32_e64 v75, v75, v235, s[96:97]
.Lpq1_12:
	ds_write_b64 v68, v[74:75] offset:43200
	v_and_b32_e32 v75, 0xffff0000, v14
	v_lshlrev_b32_e32 v74, 16, v14
	v_pk_add_f32 v[72:73], v[72:73], v[74:75] neg_lo:[0,1] neg_hi:[0,1]
	s_nop 0
	v_pk_fma_f32 v[72:73], v[66:67], v[72:73], v[74:75]
	s_cbranch_scc1 .Lpq1_13
	v_pk_mul_f32 v[234:235], v[72:73], v[236:237] op_sel_hi:[1,0]
	v_mul_f32_e32 v234, 0xbfb8aa3b, v234
	v_mul_f32_e32 v235, 0xbfb8aa3b, v235
	v_exp_f32_e32 v234, v234
	v_exp_f32_e32 v235, v235
	s_nop 0
	v_pk_add_f32 v[234:235], v[234:235], 1.0 op_sel_hi:[1,0]
	v_rcp_f32_e32 v234, v234
	v_rcp_f32_e32 v235, v235
	s_nop 0
	v_pk_fma_f32 v[234:235], v[234:235], v[236:237], v[238:239] op_sel_hi:[1,0,0]
	v_cndmask_b32_e64 v72, v72, v234, s[96:97]
	v_cndmask_b32_e64 v73, v73, v235, s[96:97]
.Lpq1_13:
	ds_write_b64 v68, v[72:73] offset:46800
	v_and_b32_e32 v73, 0xffff0000, v15
	v_lshlrev_b32_e32 v72, 16, v15
	v_pk_add_f32 v[74:75], v[74:75], v[72:73] neg_lo:[0,1] neg_hi:[0,1]
	s_nop 0
	v_pk_fma_f32 v[74:75], v[66:67], v[74:75], v[72:73]
	s_cbranch_scc1 .Lpq1_14
	v_pk_mul_f32 v[234:235], v[74:75], v[236:237] op_sel_hi:[1,0]
	v_mul_f32_e32 v234, 0xbfb8aa3b, v234
	v_mul_f32_e32 v235, 0xbfb8aa3b, v235
	v_exp_f32_e32 v234, v234
	v_exp_f32_e32 v235, v235
	s_nop 0
	v_pk_add_f32 v[234:235], v[234:235], 1.0 op_sel_hi:[1,0]
	v_rcp_f32_e32 v234, v234
	v_rcp_f32_e32 v235, v235
	s_nop 0
	v_pk_fma_f32 v[234:235], v[234:235], v[236:237], v[238:239] op_sel_hi:[1,0,0]
	v_cndmask_b32_e64 v74, v74, v234, s[96:97]
	v_cndmask_b32_e64 v75, v75, v235, s[96:97]
.Lpq1_14:
	ds_write_b64 v68, v[74:75] offset:50400
	v_and_b32_e32 v75, 0xffff0000, v16
	v_lshlrev_b32_e32 v74, 16, v16
	v_pk_add_f32 v[72:73], v[72:73], v[74:75] neg_lo:[0,1] neg_hi:[0,1]
	s_nop 0
	v_pk_fma_f32 v[72:73], v[66:67], v[72:73], v[74:75]
	s_cbranch_scc1 .Lpq1_15
	v_pk_mul_f32 v[234:235], v[72:73], v[236:237] op_sel_hi:[1,0]
	v_mul_f32_e32 v234, 0xbfb8aa3b, v234
	v_mul_f32_e32 v235, 0xbfb8aa3b, v235
	v_exp_f32_e32 v234, v234
	v_exp_f32_e32 v235, v235
	s_nop 0
	v_pk_add_f32 v[234:235], v[234:235], 1.0 op_sel_hi:[1,0]
	v_rcp_f32_e32 v234, v234
	v_rcp_f32_e32 v235, v235
	s_nop 0
	v_pk_fma_f32 v[234:235], v[234:235], v[236:237], v[238:239] op_sel_hi:[1,0,0]
	v_cndmask_b32_e64 v72, v72, v234, s[96:97]
	v_cndmask_b32_e64 v73, v73, v235, s[96:97]
.Lpq1_15:
	s_and_b64 s[4:5], s[46:47], exec
	s_cselect_b32 s4, s55, -1
	s_cmp_lt_i32 s4, 0
	ds_write_b64 v68, v[72:73] offset:54000
	s_cbranch_scc1 .LBB0_1183
	s_lshl_b32 s10, s4, 4
	s_and_b32 s4, s4, 0xff
	s_cmp_lg_u32 s4, 0
	v_ashrrev_i32_e32 v71, 31, v70
	s_cbranch_scc0 .LBB0_1207
	s_add_i32 s4, s10, -1
	s_mov_b32 s5, s11
	s_lshl_b64 s[4:5], s[4:5], 11
	s_add_u32 s4, s8, s4
	s_addc_u32 s5, s9, s5
	v_lshl_add_u64 v[0:1], v[70:71], 1, s[4:5]
	global_load_dword v0, v[0:1], off
	s_cbranch_execnz .LBB0_1182

	.amdhsa_kernel _Z9hymba_fwd6Params
		.amdhsa_group_segment_fixed_size 0
		.amdhsa_private_segment_fixed_size 0
		.amdhsa_kernarg_size 488
		.amdhsa_user_sgpr_count 2
		.amdhsa_user_sgpr_dispatch_ptr 0
		.amdhsa_user_sgpr_queue_ptr 0
		.amdhsa_user_sgpr_kernarg_segment_ptr 1
		.amdhsa_user_sgpr_dispatch_id 0
		.amdhsa_user_sgpr_kernarg_preload_length 0
		.amdhsa_user_sgpr_kernarg_preload_offset 0
		.amdhsa_user_sgpr_private_segment_size 0
		.amdhsa_uses_dynamic_stack 0
		.amdhsa_enable_private_segment 0
		.amdhsa_system_sgpr_workgroup_id_x 1
		.amdhsa_system_sgpr_workgroup_id_y 0
		.amdhsa_system_sgpr_workgroup_id_z 0
		.amdhsa_system_sgpr_workgroup_info 0
		.amdhsa_system_vgpr_workitem_id 2
		.amdhsa_next_free_vgpr 240
		.amdhsa_next_free_sgpr 100
		.amdhsa_accum_offset 240
		.amdhsa_reserve_vcc 1
		.amdhsa_float_round_mode_32 0
		.amdhsa_float_round_mode_16_64 0
		.amdhsa_float_denorm_mode_32 3
		.amdhsa_float_denorm_mode_16_64 3
		.amdhsa_dx10_clamp 1
		.amdhsa_ieee_mode 1
		.amdhsa_fp16_overflow 0
		.amdhsa_tg_split 0
		.amdhsa_exception_fp_ieee_invalid_op 0
		.amdhsa_exception_fp_denorm_src 0
		.amdhsa_exception_fp_ieee_div_zero 0
		.amdhsa_exception_fp_ieee_overflow 0
		.amdhsa_exception_fp_ieee_underflow 0
		.amdhsa_exception_fp_ieee_inexact 0
		.amdhsa_exception_int_div_zero 0
	.end_amdhsa_kernel

amdhsa.kernels:
  - .agpr_count:     0
    .args:
      - .offset:         0
        .size:           232
        .value_kind:     by_value
      - .offset:         232
        .size:           4
        .value_kind:     hidden_block_count_x
      - .offset:         236
        .size:           4
        .value_kind:     hidden_block_count_y
      - .offset:         240
        .size:           4
        .value_kind:     hidden_block_count_z
      - .offset:         244
        .size:           2
        .value_kind:     hidden_group_size_x
      - .offset:         246
        .size:           2
        .value_kind:     hidden_group_size_y
      - .offset:         248
        .size:           2
        .value_kind:     hidden_group_size_z
      - .offset:         250
        .size:           2
        .value_kind:     hidden_remainder_x
      - .offset:         252
        .size:           2
        .value_kind:     hidden_remainder_y
      - .offset:         254
        .size:           2
        .value_kind:     hidden_remainder_z
      - .offset:         272
        .size:           8
        .value_kind:     hidden_global_offset_x
      - .offset:         280
        .size:           8
        .value_kind:     hidden_global_offset_y
      - .offset:         288
        .size:           8
        .value_kind:     hidden_global_offset_z
      - .offset:         296
        .size:           2
        .value_kind:     hidden_grid_dims
      - .offset:         320
        .size:           8
        .value_kind:     hidden_multigrid_sync_arg
      - .offset:         352
        .size:           4
        .value_kind:     hidden_dynamic_lds_size
    .group_segment_fixed_size: 0
    .kernarg_segment_align: 8
    .kernarg_segment_size: 488
    .language:       OpenCL C
    .language_version:
      - 2
      - 0
    .max_flat_workgroup_size: 512
    .name:           _Z9hymba_fwd6Params
    .private_segment_fixed_size: 0
    .sgpr_count:     106
    .sgpr_spill_count: 4
    .symbol:         _Z9hymba_fwd6Params.kd
    .uniform_work_group_size: 1
    .uses_dynamic_stack: false
    .vgpr_count:     240
    .vgpr_spill_count: 0
    .wavefront_size: 64
